# phase 9a: second gla_sample item of WGs 256..383 (3 gla_grp items, second-dispatched) moved to WGs 384..511 (2 gla_grp items)
# speedup vs baseline: 1.0058x; 1.0021x over previous
.LBB0_2078:
	v_readlane_b32 s1, v250, 19
	v_readlane_b32 s0, v250, 9
	s_mov_b32 s99, 0
	s_sub_i32 s0, s0, 0x100
	s_cmp_lt_u32 s0, 0x80
	s_cselect_b32 s99, 2, 0
	s_sub_i32 s0, s0, 0x80
	s_cmp_lt_u32 s0, 0x80
	s_cselect_b32 s99, 1, s99
	s_cmpk_gt_i32 s1, 0x3ff
	s_cbranch_scc1 .LBB0_2087
	s_branch .Lgs_pre
.Lgs_done:
	s_cmp_lg_u32 s99, 1
	s_cbranch_scc1 .LBB0_2087
	s_mov_b32 s99, 0
	v_readlane_b32 s1, v250, 19
	s_add_i32 s1, s1, 0x280
.Lgs_pre:
	s_mov_b32 s15, 0
	v_mov_b32_e32 v65, 0
	s_mov_b32 s20, 0xbfb8aa3b
	v_mov_b32_e32 v81, 0x3ecc95a3
	v_mov_b32_e32 v104, 0x7f800000
	s_branch .LBB0_2081
.LBB0_2080:
	s_or_b64 exec, exec, s[0:1]
	v_readlane_b32 s0, v252, 2
	v_readlane_b32 s1, v252, 3
	s_add_i32 s1, s28, s0
	s_cmp_eq_u32 s99, 2
	s_cselect_b32 s1, 0x7fff, s1
	s_cmpk_gt_i32 s1, 0x3ff
	s_barrier
	s_cbranch_scc1 .Lgs_done
